# staging waves pace their LDS write bursts (s_sleep between timestep groups)
# speedup vs baseline: 1.0030x; 1.0030x over previous
.LBB0_696:
	v_add_u32_e32 v8, s6, v84
	v_add_u32_e32 v9, 60, v8
	v_add_u32_e32 v11, 0x54, v8
	v_min_i32_e32 v48, 0x100f, v9
	v_add_u32_e32 v47, 0x44, v8
	v_add_u32_e32 v132, 0x4c, v8
	s_bitcmp0_b32 s7, 0
	s_mov_b64 vcc, -1
	v_min_i32_e32 v8, 0x100f, v11
	v_ashrrev_i32_e32 v49, 31, v48
	v_min_i32_e32 v46, 0x100f, v47
	v_min_i32_e32 v10, 0x100f, v132
	v_med3_i32 v135, v9, 1, v217
	v_med3_i32 v134, v47, 1, v217
	v_med3_i32 v133, v132, 1, v217
	v_med3_i32 v132, v11, 1, v217
	s_cbranch_scc1 .LBB0_698
	v_ashrrev_i32_e32 v9, 31, v8
	v_ashrrev_i32_e32 v47, 31, v46
	v_ashrrev_i32_e32 v11, 31, v10
	v_lshl_add_u64 v[136:137], s[88:89], 0, v[8:9]
	v_lshl_add_u64 v[154:155], s[88:89], 0, v[48:49]
	v_lshl_add_u64 v[152:153], s[88:89], 0, v[46:47]
	v_lshl_add_u64 v[148:149], s[88:89], 0, v[10:11]
	v_lshlrev_b64 v[138:139], 10, v[136:137]
	v_lshlrev_b64 v[144:145], 12, v[136:137]
	v_lshlrev_b64 v[156:157], 12, v[154:155]
	v_lshlrev_b64 v[174:175], 12, v[152:153]
	v_lshlrev_b64 v[150:151], 12, v[148:149]
	v_lshl_add_u64 v[138:139], v[4:5], 0, v[138:139]
	v_lshl_add_u64 v[146:147], v[0:1], 0, v[144:145]
	v_lshl_add_u64 v[158:159], v[0:1], 0, v[156:157]
	v_lshl_add_u64 v[176:177], v[0:1], 0, v[174:175]
	v_lshl_add_u64 v[178:179], v[0:1], 0, v[150:151]
	v_lshl_add_u64 v[144:145], v[6:7], 0, v[144:145]
	v_add_u32_e32 v162, -1, v135
	global_load_dword v9, v[138:139], off
	global_load_dword v136, v[146:147], off offset:1024
	global_load_dword v140, v[176:177], off
	v_lshlrev_b64 v[152:153], 10, v[152:153]
	global_load_dword v139, v[158:159], off
	global_load_dword v141, v[178:179], off
	global_load_dword v142, v[146:147], off
	global_load_dword v143, v[144:145], off offset:3072
	s_nop 0
	global_load_dword v144, v[146:147], off offset:3072
	v_lshl_add_u64 v[146:147], s[88:89], 0, v[162:163]
	v_lshlrev_b64 v[146:147], 10, v[146:147]
	v_lshl_add_u64 v[146:147], v[2:3], 0, v[146:147]
	v_add_u32_e32 v162, -1, v134
	global_load_dword v11, v[146:147], off
	v_lshl_add_u64 v[146:147], s[88:89], 0, v[162:163]
	v_lshlrev_b64 v[146:147], 10, v[146:147]
	v_lshl_add_u64 v[146:147], v[2:3], 0, v[146:147]
	v_add_u32_e32 v162, -1, v133
	global_load_dword v47, v[146:147], off
	v_lshl_add_u64 v[146:147], s[88:89], 0, v[162:163]
	v_lshlrev_b64 v[146:147], 10, v[146:147]
	v_lshl_add_u64 v[146:147], v[2:3], 0, v[146:147]
	v_add_u32_e32 v162, -1, v132
	global_load_dword v137, v[146:147], off
	v_lshl_add_u64 v[146:147], s[88:89], 0, v[162:163]
	v_lshlrev_b64 v[146:147], 10, v[146:147]
	v_lshl_add_u64 v[146:147], v[2:3], 0, v[146:147]
	global_load_dword v138, v[146:147], off
	v_lshlrev_b64 v[146:147], 10, v[148:149]
	v_lshl_add_u64 v[146:147], v[4:5], 0, v[146:147]
	v_lshl_add_u64 v[148:149], v[6:7], 0, v[150:151]
	v_lshl_add_u64 v[152:153], v[4:5], 0, v[152:153]
	v_lshlrev_b64 v[154:155], 10, v[154:155]
	global_load_dword v145, v[146:147], off
	s_nop 0
	global_load_dword v146, v[178:179], off offset:1024
	s_nop 0
	global_load_dword v148, v[148:149], off offset:3072
	s_nop 0
	global_load_dword v151, v[178:179], off offset:3072
	global_load_dword v147, v[152:153], off
	global_load_dword v149, v[176:177], off offset:1024
	v_lshl_add_u64 v[152:153], v[6:7], 0, v[174:175]
	v_lshl_add_u64 v[154:155], v[4:5], 0, v[154:155]
	v_lshl_add_u64 v[156:157], v[6:7], 0, v[156:157]
	global_load_dword v152, v[152:153], off offset:3072
	s_nop 0
	global_load_dword v153, v[176:177], off offset:3072
	global_load_dword v150, v[154:155], off
	s_nop 0
	global_load_dword v154, v[158:159], off offset:1024
	global_load_dword v155, v[156:157], off offset:3072
	s_nop 0
	global_load_dword v156, v[158:159], off offset:3072
	v_lshlrev_b32_e32 v157, 16, v94
	v_mul_f32_e32 v157, 0xbfb8aa3b, v157
	v_exp_f32_e32 v178, v157
	v_and_b32_e32 v157, 0xffff0000, v94
	v_mul_f32_e32 v157, 0xbfb8aa3b, v157
	v_exp_f32_e32 v179, v157
	v_lshlrev_b32_e32 v180, 16, v90
	v_and_b32_e32 v181, 0xffff0000, v90
	v_lshlrev_b32_e32 v157, 16, v93
	ds_write_b128 v64, v[178:181]
	v_lshlrev_b32_e32 v178, 16, v53
	v_lshlrev_b32_e32 v179, 16, v98
	v_and_b32_e32 v180, 0xffff0000, v53
	v_and_b32_e32 v181, 0xffff0000, v98
	v_mul_f32_e32 v157, 0xbfb8aa3b, v157
	ds_write_b128 v64, v[178:181] offset:16384
	v_exp_f32_e32 v178, v157
	v_and_b32_e32 v157, 0xffff0000, v93
	v_mul_f32_e32 v157, 0xbfb8aa3b, v157
	v_exp_f32_e32 v179, v157
	v_lshlrev_b32_e32 v158, 16, v51
	v_and_b32_e32 v159, 0xffff0000, v51
	ds_write_b64 v65, v[158:159] offset:32768
	v_lshlrev_b32_e32 v158, 16, v50
	v_and_b32_e32 v159, 0xffff0000, v50
	v_lshlrev_b32_e32 v180, 16, v87
	v_and_b32_e32 v181, 0xffff0000, v87
	v_lshlrev_b32_e32 v157, 16, v100
	ds_write_b64 v116, v[158:159] offset:49152
	s_sleep 5
	ds_write_b128 v67, v[178:181]
	v_lshlrev_b32_e32 v178, 16, v91
	v_lshlrev_b32_e32 v179, 16, v99
	v_and_b32_e32 v180, 0xffff0000, v91
	v_and_b32_e32 v181, 0xffff0000, v99
	v_mul_f32_e32 v157, 0xbfb8aa3b, v157
	ds_write_b128 v67, v[178:181] offset:16384
	v_exp_f32_e32 v178, v157
	v_and_b32_e32 v157, 0xffff0000, v100
	v_mul_f32_e32 v157, 0xbfb8aa3b, v157
	v_exp_f32_e32 v179, v157
	v_lshlrev_b32_e32 v158, 16, v54
	v_and_b32_e32 v159, 0xffff0000, v54
	ds_write_b64 v68, v[158:159] offset:32768
	v_lshlrev_b32_e32 v158, 16, v52
	v_and_b32_e32 v159, 0xffff0000, v52
	v_lshlrev_b32_e32 v180, 16, v96
	v_and_b32_e32 v181, 0xffff0000, v96
	v_lshlrev_b32_e32 v157, 16, v101
	ds_write_b64 v117, v[158:159] offset:49152
	s_sleep 5
	ds_write_b128 v70, v[178:181]
	v_lshlrev_b32_e32 v178, 16, v95
	v_lshlrev_b32_e32 v179, 16, v102
	v_and_b32_e32 v180, 0xffff0000, v95
	v_and_b32_e32 v181, 0xffff0000, v102
	v_mul_f32_e32 v157, 0xbfb8aa3b, v157
	ds_write_b128 v70, v[178:181] offset:16384
	v_exp_f32_e32 v178, v157
	v_and_b32_e32 v157, 0xffff0000, v101
	v_mul_f32_e32 v157, 0xbfb8aa3b, v157
	v_exp_f32_e32 v179, v157
	v_lshlrev_b32_e32 v158, 16, v88
	v_and_b32_e32 v159, 0xffff0000, v88
	ds_write_b64 v71, v[158:159] offset:32768
	v_lshlrev_b32_e32 v158, 16, v55
	v_and_b32_e32 v159, 0xffff0000, v55
	v_lshlrev_b32_e32 v180, 16, v97
	v_and_b32_e32 v181, 0xffff0000, v97
	ds_write_b64 v119, v[158:159] offset:49152
	s_sleep 5
	ds_write_b128 v73, v[178:181]
	v_lshlrev_b32_e32 v178, 16, v92
	v_lshlrev_b32_e32 v179, 16, v103
	v_and_b32_e32 v180, 0xffff0000, v92
	v_and_b32_e32 v181, 0xffff0000, v103
	v_lshlrev_b32_e32 v158, 16, v89
	v_and_b32_e32 v159, 0xffff0000, v89
	ds_write_b128 v73, v[178:181] offset:16384
	ds_write_b64 v74, v[158:159] offset:32768
	v_lshlrev_b32_e32 v158, 16, v86
	v_and_b32_e32 v159, 0xffff0000, v86
	s_mov_b64 vcc, 0
	ds_write_b64 v118, v[158:159] offset:49152
.LBB0_698:
	s_andn2_b64 vcc, exec, vcc
	s_cbranch_vccnz .LBB0_700
	s_waitcnt vmcnt(14)
	v_ashrrev_i32_e32 v47, 31, v46
	v_ashrrev_i32_e32 v11, 31, v10
	v_ashrrev_i32_e32 v9, 31, v8
	v_lshl_add_u64 v[48:49], s[88:89], 0, v[48:49]
	v_lshl_add_u64 v[46:47], s[88:89], 0, v[46:47]
	v_lshl_add_u64 v[10:11], s[88:89], 0, v[10:11]
	v_lshl_add_u64 v[8:9], s[88:89], 0, v[8:9]
	v_lshlrev_b64 v[50:51], 10, v[48:49]
	v_lshlrev_b64 v[52:53], 10, v[46:47]
	v_lshlrev_b64 v[54:55], 10, v[10:11]
	v_lshlrev_b64 v[86:87], 10, v[8:9]
	v_lshlrev_b64 v[48:49], 12, v[48:49]
	v_lshlrev_b64 v[46:47], 12, v[46:47]
	v_lshlrev_b64 v[10:11], 12, v[10:11]
	v_lshlrev_b64 v[8:9], 12, v[8:9]
	v_lshl_add_u64 v[50:51], v[4:5], 0, v[50:51]
	v_lshl_add_u64 v[52:53], v[4:5], 0, v[52:53]
	v_lshl_add_u64 v[54:55], v[4:5], 0, v[54:55]
	v_lshl_add_u64 v[86:87], v[4:5], 0, v[86:87]
	v_lshl_add_u64 v[98:99], v[0:1], 0, v[48:49]
	v_lshl_add_u64 v[100:101], v[0:1], 0, v[46:47]
	v_lshl_add_u64 v[102:103], v[0:1], 0, v[10:11]
	s_waitcnt vmcnt(13)
	v_lshl_add_u64 v[136:137], v[0:1], 0, v[8:9]
	v_lshl_add_u64 v[48:49], v[6:7], 0, v[48:49]
	v_lshl_add_u64 v[46:47], v[6:7], 0, v[46:47]
	v_lshl_add_u64 v[10:11], v[6:7], 0, v[10:11]
	v_lshl_add_u64 v[8:9], v[6:7], 0, v[8:9]
	v_add_u32_e32 v162, -1, v135
	global_load_dword v50, v[50:51], off
	s_waitcnt vmcnt(5)
	v_mov_b32_e32 v144, v127
	global_load_dword v52, v[52:53], off
	v_mov_b32_e32 v151, v121
	global_load_dword v55, v[54:55], off
	v_mov_b32_e32 v153, v110
	global_load_dword v86, v[86:87], off
	s_waitcnt vmcnt(4)
	v_mov_b32_e32 v156, v105
	global_load_dword v88, v[102:103], off offset:1024
	global_load_dword v51, v[98:99], off offset:1024
	global_load_dword v54, v[100:101], off offset:1024
	global_load_dword v89, v[136:137], off offset:1024
	global_load_dword v53, v[98:99], off
	global_load_dword v91, v[100:101], off
	global_load_dword v95, v[102:103], off
	global_load_dword v92, v[136:137], off
	global_load_dword v90, v[48:49], off offset:3072
	global_load_dword v87, v[46:47], off offset:3072
	global_load_dword v96, v[10:11], off offset:3072
	global_load_dword v97, v[8:9], off offset:3072
	global_load_dword v94, v[98:99], off offset:3072
	global_load_dword v93, v[100:101], off offset:3072
	s_nop 0
	global_load_dword v100, v[102:103], off offset:3072
	global_load_dword v101, v[136:137], off offset:3072
	v_lshl_add_u64 v[8:9], s[88:89], 0, v[162:163]
	v_lshlrev_b64 v[8:9], 10, v[8:9]
	v_lshl_add_u64 v[8:9], v[2:3], 0, v[8:9]
	v_add_u32_e32 v162, -1, v134
	global_load_dword v98, v[8:9], off
	v_lshl_add_u64 v[8:9], s[88:89], 0, v[162:163]
	v_lshlrev_b64 v[8:9], 10, v[8:9]
	v_lshl_add_u64 v[8:9], v[2:3], 0, v[8:9]
	v_add_u32_e32 v162, -1, v133
	global_load_dword v99, v[8:9], off
	v_lshl_add_u64 v[8:9], s[88:89], 0, v[162:163]
	v_lshlrev_b64 v[8:9], 10, v[8:9]
	v_lshl_add_u64 v[8:9], v[2:3], 0, v[8:9]
	v_add_u32_e32 v162, -1, v132
	global_load_dword v102, v[8:9], off
	v_lshl_add_u64 v[8:9], s[88:89], 0, v[162:163]
	v_lshlrev_b64 v[8:9], 10, v[8:9]
	v_lshl_add_u64 v[8:9], v[2:3], 0, v[8:9]
	global_load_dword v103, v[8:9], off
	v_lshlrev_b32_e32 v8, 16, v105
	v_and_b32_e32 v9, 0xffff0000, v105
	v_mul_f32_e32 v8, 0xbfb8aa3b, v8
	v_mul_f32_e32 v9, 0xbfb8aa3b, v9
	v_exp_f32_e32 v8, v8
	v_exp_f32_e32 v9, v9
	v_lshlrev_b32_e32 v10, 16, v106
	v_and_b32_e32 v11, 0xffff0000, v106
	v_mov_b32_e32 v143, v128
	ds_write_b128 v64, v[8:11] offset:57344
	v_lshlrev_b32_e32 v8, 16, v104
	v_lshlrev_b32_e32 v9, 16, v109
	v_and_b32_e32 v10, 0xffff0000, v104
	v_and_b32_e32 v11, 0xffff0000, v109
	ds_write_b128 v76, v[8:11]
	v_lshlrev_b32_e32 v8, 16, v107
	v_and_b32_e32 v9, 0xffff0000, v107
	ds_write_b64 v77, v[8:9]
	v_lshlrev_b32_e32 v8, 16, v108
	v_and_b32_e32 v9, 0xffff0000, v108
	v_add_u32_e32 v10, v63, v66
	ds_write_b64 v10, v[8:9]
	v_lshlrev_b32_e32 v8, 16, v110
	v_and_b32_e32 v9, 0xffff0000, v110
	v_mul_f32_e32 v8, 0xbfb8aa3b, v8
	v_mul_f32_e32 v9, 0xbfb8aa3b, v9
	v_exp_f32_e32 v8, v8
	v_exp_f32_e32 v9, v9
	v_lshlrev_b32_e32 v10, 16, v111
	v_and_b32_e32 v11, 0xffff0000, v111
	v_mov_b32_e32 v148, v122
	s_sleep 5
	ds_write_b128 v67, v[8:11] offset:57344
	v_lshlrev_b32_e32 v8, 16, v112
	v_lshlrev_b32_e32 v9, 16, v113
	v_and_b32_e32 v10, 0xffff0000, v112
	v_and_b32_e32 v11, 0xffff0000, v113
	ds_write_b128 v78, v[8:11]
	v_lshlrev_b32_e32 v8, 16, v114
	v_and_b32_e32 v9, 0xffff0000, v114
	ds_write_b64 v79, v[8:9]
	v_lshlrev_b32_e32 v8, 16, v115
	v_and_b32_e32 v9, 0xffff0000, v115
	v_add_u32_e32 v10, v63, v69
	ds_write_b64 v10, v[8:9]
	v_lshlrev_b32_e32 v8, 16, v121
	v_and_b32_e32 v9, 0xffff0000, v121
	v_mul_f32_e32 v8, 0xbfb8aa3b, v8
	v_mul_f32_e32 v9, 0xbfb8aa3b, v9
	v_exp_f32_e32 v8, v8
	v_exp_f32_e32 v9, v9
	v_lshlrev_b32_e32 v10, 16, v122
	v_and_b32_e32 v11, 0xffff0000, v122
	v_mov_b32_e32 v152, v111
	s_sleep 5
	ds_write_b128 v70, v[8:11] offset:57344
	v_lshlrev_b32_e32 v8, 16, v120
	v_lshlrev_b32_e32 v9, 16, v126
	v_and_b32_e32 v10, 0xffff0000, v120
	v_and_b32_e32 v11, 0xffff0000, v126
	ds_write_b128 v80, v[8:11]
	v_lshlrev_b32_e32 v8, 16, v123
	v_and_b32_e32 v9, 0xffff0000, v123
	ds_write_b64 v81, v[8:9]
	v_lshlrev_b32_e32 v8, 16, v124
	v_and_b32_e32 v9, 0xffff0000, v124
	v_add_u32_e32 v10, v63, v72
	ds_write_b64 v10, v[8:9]
	v_lshlrev_b32_e32 v8, 16, v127
	v_and_b32_e32 v9, 0xffff0000, v127
	v_mul_f32_e32 v8, 0xbfb8aa3b, v8
	v_mul_f32_e32 v9, 0xbfb8aa3b, v9
	v_exp_f32_e32 v8, v8
	v_exp_f32_e32 v9, v9
	v_lshlrev_b32_e32 v10, 16, v128
	v_and_b32_e32 v11, 0xffff0000, v128
	v_mov_b32_e32 v155, v106
	s_sleep 5
	ds_write_b128 v73, v[8:11] offset:57344
	v_lshlrev_b32_e32 v8, 16, v125
	v_lshlrev_b32_e32 v9, 16, v131
	v_and_b32_e32 v10, 0xffff0000, v125
	v_and_b32_e32 v11, 0xffff0000, v131
	ds_write_b128 v82, v[8:11]
	v_lshlrev_b32_e32 v8, 16, v129
	v_and_b32_e32 v9, 0xffff0000, v129
	ds_write_b64 v83, v[8:9]
	v_lshlrev_b32_e32 v8, 16, v130
	v_and_b32_e32 v9, 0xffff0000, v130
	v_add_u32_e32 v10, v63, v75
	ds_write_b64 v10, v[8:9]
	v_mov_b32_e32 v136, v129
	v_mov_b32_e32 v146, v123
	v_mov_b32_e32 v149, v114
	v_mov_b32_e32 v154, v107
	v_mov_b32_e32 v9, v130
	v_mov_b32_e32 v145, v124
	v_mov_b32_e32 v147, v115
	v_mov_b32_e32 v150, v108
	v_mov_b32_e32 v11, v109
	v_mov_b32_e32 v47, v113
	v_mov_b32_e32 v137, v126
	v_mov_b32_e32 v138, v131
	v_mov_b32_e32 v139, v104
	v_mov_b32_e32 v140, v112
	v_mov_b32_e32 v141, v120
	v_mov_b32_e32 v142, v125
